# nt (streaming) hint on the residual-stream stores of the two Resid GEMM epilogues (wout, mlp2), on top of v76 conv/attn/prep/G2/mlp1 scheduling changes
# baseline (speedup 1.0000x reference)
.LBB0_413:
	s_ashr_i32 s3, s2, 31
	s_lshl_b64 s[2:3], s[2:3], 8
	v_lshl_add_u64 v[156:157], s[2:3], 0, v[150:151]
	v_readlane_b32 s28, v253, 40
	s_lshl_b32 s2, s37, 8
	v_cmp_lt_i32_e32 vcc, v192, v187
	v_lshlrev_b64 v[136:137], 11, v[156:157]
	v_readlane_b32 s29, v253, 41
	s_ashr_i32 s3, s2, 31
	v_cndmask_b32_e32 v0, v186, v192, vcc
	v_cmp_lt_i32_e32 vcc, v193, v187
	v_lshl_add_u64 v[136:137], s[28:29], 0, v[136:137]
	v_readlane_b32 s28, v254, 59
	v_lshlrev_b32_e32 v161, 2, v0
	v_cndmask_b32_e32 v0, v186, v193, vcc
	v_lshl_add_u64 v[136:137], s[2:3], 1, v[136:137]
	s_lshl_b32 s94, s28, 1
	v_lshlrev_b32_e32 v160, 2, v0
	v_lshl_add_u64 v[136:137], v[136:137], 0, s[94:95]
	v_lshlrev_b32_e32 v0, 1, v148
	v_lshl_add_u64 v[158:159], v[136:137], 0, v[0:1]
	global_load_dwordx4 v[162:165], v[158:159], off
	s_lshl_b32 s42, s37, 2
	s_ashr_i32 s43, s42, 31
	s_waitcnt vmcnt(0)
	v_lshlrev_b32_e32 v136, 16, v162
	v_and_b32_e32 v137, 0xffff0000, v162
	v_pk_add_f32 v[126:127], v[126:127], v[136:137]
	v_lshlrev_b32_e32 v136, 16, v163
	v_and_b32_e32 v137, 0xffff0000, v163
	v_pk_add_f32 v[136:137], v[128:129], v[136:137]
	v_lshlrev_b32_e32 v128, 16, v164
	v_and_b32_e32 v129, 0xffff0000, v164
	v_pk_add_f32 v[138:139], v[122:123], v[128:129]
	v_lshlrev_b32_e32 v122, 16, v165
	v_and_b32_e32 v123, 0xffff0000, v165
	v_pk_add_f32 v[162:163], v[124:125], v[122:123]
	v_cvt_pk_bf16_f32 v122, v126, v127
	v_cvt_pk_bf16_f32 v123, v136, v137
	v_cvt_pk_bf16_f32 v124, v138, v139
	v_cvt_pk_bf16_f32 v125, v162, v163
	global_store_dwordx4 v[158:159], v[122:125], off nt
	v_pk_mul_f32 v[128:129], v[126:127], v[126:127]
	v_pk_mul_f32 v[126:127], v[136:137], v[136:137]
	v_pk_mul_f32 v[122:123], v[162:163], v[162:163]
	global_load_dwordx4 v[162:165], v[158:159], off offset:256
	v_pk_mul_f32 v[124:125], v[138:139], v[138:139]
	s_waitcnt vmcnt(0)
	v_lshlrev_b32_e32 v136, 16, v162
	v_and_b32_e32 v137, 0xffff0000, v162
	v_pk_add_f32 v[118:119], v[118:119], v[136:137]
	v_lshlrev_b32_e32 v136, 16, v163
	v_and_b32_e32 v137, 0xffff0000, v163
	v_pk_add_f32 v[120:121], v[120:121], v[136:137]
	v_lshlrev_b32_e32 v136, 16, v164
	v_and_b32_e32 v137, 0xffff0000, v164
	v_pk_add_f32 v[136:137], v[114:115], v[136:137]
	v_lshlrev_b32_e32 v114, 16, v165
	v_and_b32_e32 v115, 0xffff0000, v165
	v_pk_add_f32 v[138:139], v[116:117], v[114:115]
	v_cvt_pk_bf16_f32 v114, v118, v119
	v_cvt_pk_bf16_f32 v115, v120, v121
	v_cvt_pk_bf16_f32 v116, v136, v137
	v_cvt_pk_bf16_f32 v117, v138, v139
	global_store_dwordx4 v[158:159], v[114:117], off offset:256 nt
	s_nop 1
	v_pk_mul_f32 v[114:115], v[118:119], v[118:119]
	v_pk_mul_f32 v[116:117], v[120:121], v[120:121]
	v_add_f32_e32 v114, v114, v115
	v_add_f32_e32 v115, v128, v129
	v_add_f32_e32 v114, v116, v114
	v_add_f32_e32 v115, v126, v115
	v_pk_mul_f32 v[118:119], v[136:137], v[136:137]
	v_add_f32_e32 v114, v117, v114
	v_add_f32_e32 v115, v127, v115
	v_add_f32_e32 v114, v118, v114
	v_add_f32_e32 v115, v124, v115
	v_pk_mul_f32 v[120:121], v[138:139], v[138:139]
	v_add_f32_e32 v114, v119, v114
	v_add_f32_e32 v115, v125, v115
	v_add_f32_e32 v114, v120, v114
	v_add_f32_e32 v115, v122, v115
	v_add_f32_e32 v114, v121, v114
	v_add_f32_e32 v115, v123, v115
	v_add_f32_e32 v114, v115, v114
	ds_bpermute_b32 v115, v161, v114
	s_waitcnt lgkmcnt(0)
	v_add_f32_e32 v114, v114, v115
	ds_bpermute_b32 v115, v160, v114
	s_and_saveexec_b64 s[28:29], s[38:39]
	v_readlane_b32 s82, v254, 31
	v_readlane_b32 s83, v254, 32
	s_cbranch_execz .LBB0_415
	v_readlane_b32 s52, v252, 41
	v_lshlrev_b64 v[116:117], 6, v[156:157]
	v_readlane_b32 s53, v252, 42
	s_waitcnt lgkmcnt(0)
	v_add_f32_e32 v114, v114, v115
	v_lshl_add_u64 v[116:117], s[52:53], 0, v[116:117]
	v_lshl_add_u64 v[116:117], s[42:43], 2, v[116:117]
	s_lshl_b32 s52, s92, 2
	s_mov_b32 s53, s95
	v_lshl_add_u64 v[116:117], v[116:117], 0, s[52:53]
	global_store_dword v[116:117], v114, off nt
.LBB0_415:
	s_or_b64 exec, exec, s[28:29]
	v_or_b32_e32 v114, 16, v156
	s_waitcnt lgkmcnt(0)
	v_mov_b32_e32 v115, v157
	v_readlane_b32 s28, v253, 40
	v_lshlrev_b64 v[116:117], 11, v[114:115]
	v_readlane_b32 s29, v253, 41
	s_nop 1
	v_lshl_add_u64 v[116:117], s[28:29], 0, v[116:117]
	v_lshl_add_u64 v[116:117], s[2:3], 1, v[116:117]
	v_lshl_add_u64 v[116:117], v[116:117], 0, s[94:95]
	v_lshl_add_u64 v[120:121], v[116:117], 0, v[0:1]
	global_load_dwordx4 v[116:119], v[120:121], off
	s_waitcnt vmcnt(0)
	v_lshlrev_b32_e32 v122, 16, v116
	v_and_b32_e32 v123, 0xffff0000, v116
	v_lshlrev_b32_e32 v116, 16, v117
	v_and_b32_e32 v117, 0xffff0000, v117
	v_pk_add_f32 v[116:117], v[112:113], v[116:117]
	v_lshlrev_b32_e32 v112, 16, v118
	v_and_b32_e32 v113, 0xffff0000, v118
	v_pk_add_f32 v[110:111], v[110:111], v[122:123]
	v_pk_add_f32 v[122:123], v[106:107], v[112:113]
	v_lshlrev_b32_e32 v106, 16, v119
	v_and_b32_e32 v107, 0xffff0000, v119
	v_pk_add_f32 v[118:119], v[108:109], v[106:107]
	v_cvt_pk_bf16_f32 v106, v110, v111
	v_cvt_pk_bf16_f32 v107, v116, v117
	v_cvt_pk_bf16_f32 v108, v122, v123
	v_cvt_pk_bf16_f32 v109, v118, v119
	global_store_dwordx4 v[120:121], v[106:109], off nt
	v_pk_mul_f32 v[112:113], v[110:111], v[110:111]
	v_pk_mul_f32 v[110:111], v[116:117], v[116:117]
	v_pk_mul_f32 v[106:107], v[118:119], v[118:119]
	global_load_dwordx4 v[116:119], v[120:121], off offset:256
	v_pk_mul_f32 v[108:109], v[122:123], v[122:123]
	s_waitcnt vmcnt(0)
	v_lshlrev_b32_e32 v122, 16, v116
	v_and_b32_e32 v123, 0xffff0000, v116
	v_lshlrev_b32_e32 v116, 16, v117
	v_and_b32_e32 v117, 0xffff0000, v117
	v_pk_add_f32 v[104:105], v[104:105], v[116:117]
	v_lshlrev_b32_e32 v116, 16, v118
	v_and_b32_e32 v117, 0xffff0000, v118
	v_pk_add_f32 v[116:117], v[98:99], v[116:117]
	v_lshlrev_b32_e32 v98, 16, v119
	v_and_b32_e32 v99, 0xffff0000, v119
	v_pk_add_f32 v[102:103], v[102:103], v[122:123]
	v_pk_add_f32 v[118:119], v[100:101], v[98:99]
	v_cvt_pk_bf16_f32 v98, v102, v103
	v_cvt_pk_bf16_f32 v99, v104, v105
	v_cvt_pk_bf16_f32 v100, v116, v117
	v_cvt_pk_bf16_f32 v101, v118, v119
	global_store_dwordx4 v[120:121], v[98:101], off offset:256 nt
	s_nop 1
	v_pk_mul_f32 v[98:99], v[102:103], v[102:103]
	v_pk_mul_f32 v[100:101], v[104:105], v[104:105]
	v_add_f32_e32 v98, v98, v99
	v_add_f32_e32 v99, v112, v113
	v_add_f32_e32 v98, v100, v98
	v_add_f32_e32 v99, v110, v99
	v_pk_mul_f32 v[102:103], v[116:117], v[116:117]
	v_add_f32_e32 v98, v101, v98
	v_add_f32_e32 v99, v111, v99
	v_add_f32_e32 v98, v102, v98
	v_add_f32_e32 v99, v108, v99
	v_pk_mul_f32 v[104:105], v[118:119], v[118:119]
	v_add_f32_e32 v98, v103, v98
	v_add_f32_e32 v99, v109, v99
	v_add_f32_e32 v98, v104, v98
	v_add_f32_e32 v99, v106, v99
	v_add_f32_e32 v98, v105, v98
	v_add_f32_e32 v99, v107, v99
	v_add_f32_e32 v98, v99, v98
	ds_bpermute_b32 v99, v161, v98
	s_waitcnt lgkmcnt(0)
	v_add_f32_e32 v98, v98, v99
	ds_bpermute_b32 v99, v160, v98
	s_and_saveexec_b64 s[28:29], s[38:39]
	s_cbranch_execz .LBB0_417
	v_readlane_b32 s52, v252, 41
	v_lshlrev_b64 v[100:101], 6, v[114:115]
	v_readlane_b32 s53, v252, 42
	s_waitcnt lgkmcnt(0)
	v_add_f32_e32 v98, v98, v99
	v_lshl_add_u64 v[100:101], s[52:53], 0, v[100:101]
	v_lshl_add_u64 v[100:101], s[42:43], 2, v[100:101]
	s_lshl_b32 s52, s92, 2
	s_mov_b32 s53, s95
	v_lshl_add_u64 v[100:101], v[100:101], 0, s[52:53]
	global_store_dword v[100:101], v98, off nt
.LBB0_417:
	s_or_b64 exec, exec, s[28:29]
	v_or_b32_e32 v98, 32, v156
	s_waitcnt lgkmcnt(0)
	v_mov_b32_e32 v99, v157
	v_readlane_b32 s28, v253, 40
	v_lshlrev_b64 v[100:101], 11, v[98:99]
	v_readlane_b32 s29, v253, 41
	s_nop 1
	v_lshl_add_u64 v[100:101], s[28:29], 0, v[100:101]
	v_lshl_add_u64 v[100:101], s[2:3], 1, v[100:101]
	v_lshl_add_u64 v[100:101], v[100:101], 0, s[94:95]
	v_lshl_add_u64 v[104:105], v[100:101], 0, v[0:1]
	global_load_dwordx4 v[100:103], v[104:105], off
	s_waitcnt vmcnt(0)
	v_lshlrev_b32_e32 v106, 16, v100
	v_and_b32_e32 v107, 0xffff0000, v100
	v_lshlrev_b32_e32 v100, 16, v101
	v_and_b32_e32 v101, 0xffff0000, v101
	v_pk_add_f32 v[100:101], v[96:97], v[100:101]
	v_lshlrev_b32_e32 v96, 16, v102
	v_and_b32_e32 v97, 0xffff0000, v102
	v_pk_add_f32 v[94:95], v[94:95], v[106:107]
	v_pk_add_f32 v[106:107], v[90:91], v[96:97]
	v_lshlrev_b32_e32 v90, 16, v103
	v_and_b32_e32 v91, 0xffff0000, v103
	v_pk_add_f32 v[102:103], v[92:93], v[90:91]
	v_cvt_pk_bf16_f32 v90, v94, v95
	v_cvt_pk_bf16_f32 v91, v100, v101
	v_cvt_pk_bf16_f32 v92, v106, v107
	v_cvt_pk_bf16_f32 v93, v102, v103
	global_store_dwordx4 v[104:105], v[90:93], off nt
	v_pk_mul_f32 v[96:97], v[94:95], v[94:95]
	v_pk_mul_f32 v[94:95], v[100:101], v[100:101]
	v_pk_mul_f32 v[90:91], v[102:103], v[102:103]
	global_load_dwordx4 v[100:103], v[104:105], off offset:256
	v_pk_mul_f32 v[92:93], v[106:107], v[106:107]
	s_waitcnt vmcnt(0)
	v_lshlrev_b32_e32 v106, 16, v100
	v_and_b32_e32 v107, 0xffff0000, v100
	v_lshlrev_b32_e32 v100, 16, v101
	v_and_b32_e32 v101, 0xffff0000, v101
	v_pk_add_f32 v[88:89], v[88:89], v[100:101]
	v_lshlrev_b32_e32 v100, 16, v102
	v_and_b32_e32 v101, 0xffff0000, v102
	v_pk_add_f32 v[100:101], v[82:83], v[100:101]
	v_lshlrev_b32_e32 v82, 16, v103
	v_and_b32_e32 v83, 0xffff0000, v103
	v_pk_add_f32 v[86:87], v[86:87], v[106:107]
	v_pk_add_f32 v[102:103], v[84:85], v[82:83]
	v_cvt_pk_bf16_f32 v82, v86, v87
	v_cvt_pk_bf16_f32 v83, v88, v89
	v_cvt_pk_bf16_f32 v84, v100, v101
	v_cvt_pk_bf16_f32 v85, v102, v103
	global_store_dwordx4 v[104:105], v[82:85], off offset:256 nt
	s_nop 1
	v_pk_mul_f32 v[82:83], v[86:87], v[86:87]
	v_pk_mul_f32 v[84:85], v[88:89], v[88:89]
	v_add_f32_e32 v82, v82, v83
	v_add_f32_e32 v83, v96, v97
	v_add_f32_e32 v82, v84, v82
	v_add_f32_e32 v83, v94, v83
	v_pk_mul_f32 v[86:87], v[100:101], v[100:101]
	v_add_f32_e32 v82, v85, v82
	v_add_f32_e32 v83, v95, v83
	v_add_f32_e32 v82, v86, v82
	v_add_f32_e32 v83, v92, v83
	v_pk_mul_f32 v[88:89], v[102:103], v[102:103]
	v_add_f32_e32 v82, v87, v82
	v_add_f32_e32 v83, v93, v83
	v_add_f32_e32 v82, v88, v82
	v_add_f32_e32 v83, v90, v83
	v_add_f32_e32 v82, v89, v82
	v_add_f32_e32 v83, v91, v83
	v_add_f32_e32 v82, v83, v82
	ds_bpermute_b32 v83, v161, v82
	s_waitcnt lgkmcnt(0)
	v_add_f32_e32 v82, v82, v83
	ds_bpermute_b32 v83, v160, v82
	s_and_saveexec_b64 s[28:29], s[38:39]
	s_cbranch_execz .LBB0_419
	v_readlane_b32 s52, v252, 41
	v_lshlrev_b64 v[84:85], 6, v[98:99]
	v_readlane_b32 s53, v252, 42
	s_waitcnt lgkmcnt(0)
	v_add_f32_e32 v82, v82, v83
	v_lshl_add_u64 v[84:85], s[52:53], 0, v[84:85]
	v_lshl_add_u64 v[84:85], s[42:43], 2, v[84:85]
	s_lshl_b32 s52, s92, 2
	s_mov_b32 s53, s95
	v_lshl_add_u64 v[84:85], v[84:85], 0, s[52:53]
	global_store_dword v[84:85], v82, off nt
.LBB0_419:
	s_or_b64 exec, exec, s[28:29]
	v_or_b32_e32 v82, 48, v156
	s_waitcnt lgkmcnt(0)
	v_mov_b32_e32 v83, v157
	v_readlane_b32 s28, v253, 40
	v_lshlrev_b64 v[84:85], 11, v[82:83]
	v_readlane_b32 s29, v253, 41
	s_nop 1
	v_lshl_add_u64 v[84:85], s[28:29], 0, v[84:85]
	v_lshl_add_u64 v[84:85], s[2:3], 1, v[84:85]
	v_lshl_add_u64 v[84:85], v[84:85], 0, s[94:95]
	v_lshl_add_u64 v[88:89], v[84:85], 0, v[0:1]
	global_load_dwordx4 v[84:87], v[88:89], off
	s_waitcnt vmcnt(0)
	v_lshlrev_b32_e32 v90, 16, v84
	v_and_b32_e32 v91, 0xffff0000, v84
	v_lshlrev_b32_e32 v84, 16, v85
	v_and_b32_e32 v85, 0xffff0000, v85
	v_pk_add_f32 v[84:85], v[80:81], v[84:85]
	v_lshlrev_b32_e32 v80, 16, v86
	v_and_b32_e32 v81, 0xffff0000, v86
	v_pk_add_f32 v[78:79], v[78:79], v[90:91]
	v_pk_add_f32 v[90:91], v[74:75], v[80:81]
	v_lshlrev_b32_e32 v74, 16, v87
	v_and_b32_e32 v75, 0xffff0000, v87
	v_pk_add_f32 v[86:87], v[76:77], v[74:75]
	v_cvt_pk_bf16_f32 v74, v78, v79
	v_cvt_pk_bf16_f32 v75, v84, v85
	v_cvt_pk_bf16_f32 v76, v90, v91
	v_cvt_pk_bf16_f32 v77, v86, v87
	global_store_dwordx4 v[88:89], v[74:77], off nt
	v_pk_mul_f32 v[80:81], v[78:79], v[78:79]
	v_pk_mul_f32 v[78:79], v[84:85], v[84:85]
	v_pk_mul_f32 v[74:75], v[86:87], v[86:87]
	global_load_dwordx4 v[84:87], v[88:89], off offset:256
	v_pk_mul_f32 v[76:77], v[90:91], v[90:91]
	s_waitcnt vmcnt(0)
	v_lshlrev_b32_e32 v90, 16, v84
	v_and_b32_e32 v91, 0xffff0000, v84
	v_lshlrev_b32_e32 v84, 16, v85
	v_and_b32_e32 v85, 0xffff0000, v85
	v_pk_add_f32 v[72:73], v[72:73], v[84:85]
	v_lshlrev_b32_e32 v84, 16, v86
	v_and_b32_e32 v85, 0xffff0000, v86
	v_pk_add_f32 v[84:85], v[66:67], v[84:85]
	v_lshlrev_b32_e32 v66, 16, v87
	v_and_b32_e32 v67, 0xffff0000, v87
	v_pk_add_f32 v[70:71], v[70:71], v[90:91]
	v_pk_add_f32 v[86:87], v[68:69], v[66:67]
	v_cvt_pk_bf16_f32 v66, v70, v71
	v_cvt_pk_bf16_f32 v67, v72, v73
	v_cvt_pk_bf16_f32 v68, v84, v85
	v_cvt_pk_bf16_f32 v69, v86, v87
	global_store_dwordx4 v[88:89], v[66:69], off offset:256 nt
	s_nop 1
	v_pk_mul_f32 v[66:67], v[70:71], v[70:71]
	v_pk_mul_f32 v[68:69], v[72:73], v[72:73]
	v_add_f32_e32 v66, v66, v67
	v_add_f32_e32 v67, v80, v81
	v_add_f32_e32 v66, v68, v66
	v_add_f32_e32 v67, v78, v67
	v_pk_mul_f32 v[70:71], v[84:85], v[84:85]
	v_add_f32_e32 v66, v69, v66
	v_add_f32_e32 v67, v79, v67
	v_add_f32_e32 v66, v70, v66
	v_add_f32_e32 v67, v76, v67
	v_pk_mul_f32 v[72:73], v[86:87], v[86:87]
	v_add_f32_e32 v66, v71, v66
	v_add_f32_e32 v67, v77, v67
	v_add_f32_e32 v66, v72, v66
	v_add_f32_e32 v67, v74, v67
	v_add_f32_e32 v66, v73, v66
	v_add_f32_e32 v67, v75, v67
	v_add_f32_e32 v66, v67, v66
	ds_bpermute_b32 v67, v161, v66
	s_waitcnt lgkmcnt(0)
	v_add_f32_e32 v66, v66, v67
	ds_bpermute_b32 v67, v160, v66
	s_and_saveexec_b64 s[28:29], s[38:39]
	s_cbranch_execz .LBB0_421
	v_readlane_b32 s52, v252, 41
	v_lshlrev_b64 v[68:69], 6, v[82:83]
	v_readlane_b32 s53, v252, 42
	s_waitcnt lgkmcnt(0)
	v_add_f32_e32 v66, v66, v67
	v_lshl_add_u64 v[68:69], s[52:53], 0, v[68:69]
	v_lshl_add_u64 v[68:69], s[42:43], 2, v[68:69]
	s_lshl_b32 s52, s92, 2
	s_mov_b32 s53, s95
	v_lshl_add_u64 v[68:69], v[68:69], 0, s[52:53]
	global_store_dword v[68:69], v66, off nt
.LBB0_421:
	s_or_b64 exec, exec, s[28:29]
	s_waitcnt lgkmcnt(0)
	v_lshl_add_u64 v[66:67], v[156:157], 0, s[68:69]
	v_readlane_b32 s28, v253, 40
	v_lshlrev_b64 v[68:69], 11, v[66:67]
	v_readlane_b32 s29, v253, 41
	s_nop 1
	v_lshl_add_u64 v[68:69], s[28:29], 0, v[68:69]
	v_lshl_add_u64 v[68:69], s[2:3], 1, v[68:69]
	v_lshl_add_u64 v[68:69], v[68:69], 0, s[94:95]
	v_lshl_add_u64 v[72:73], v[68:69], 0, v[0:1]
	global_load_dwordx4 v[68:71], v[72:73], off
	s_waitcnt vmcnt(0)
	v_lshlrev_b32_e32 v74, 16, v68
	v_and_b32_e32 v75, 0xffff0000, v68
	v_lshlrev_b32_e32 v68, 16, v69
	v_and_b32_e32 v69, 0xffff0000, v69
	v_pk_add_f32 v[68:69], v[64:65], v[68:69]
	v_lshlrev_b32_e32 v64, 16, v70
	v_and_b32_e32 v65, 0xffff0000, v70
	v_pk_add_f32 v[62:63], v[62:63], v[74:75]
	v_pk_add_f32 v[74:75], v[58:59], v[64:65]
	v_lshlrev_b32_e32 v58, 16, v71
	v_and_b32_e32 v59, 0xffff0000, v71
	v_pk_add_f32 v[70:71], v[60:61], v[58:59]
	v_cvt_pk_bf16_f32 v58, v62, v63
	v_cvt_pk_bf16_f32 v59, v68, v69
	v_cvt_pk_bf16_f32 v60, v74, v75
	v_cvt_pk_bf16_f32 v61, v70, v71
	global_store_dwordx4 v[72:73], v[58:61], off nt
	v_pk_mul_f32 v[64:65], v[62:63], v[62:63]
	v_pk_mul_f32 v[62:63], v[68:69], v[68:69]
	v_pk_mul_f32 v[58:59], v[70:71], v[70:71]
	global_load_dwordx4 v[68:71], v[72:73], off offset:256
	v_pk_mul_f32 v[60:61], v[74:75], v[74:75]
	s_waitcnt vmcnt(0)
	v_lshlrev_b32_e32 v74, 16, v68
	v_and_b32_e32 v75, 0xffff0000, v68
	v_lshlrev_b32_e32 v68, 16, v69
	v_and_b32_e32 v69, 0xffff0000, v69
	v_pk_add_f32 v[56:57], v[56:57], v[68:69]
	v_lshlrev_b32_e32 v68, 16, v70
	v_and_b32_e32 v69, 0xffff0000, v70
	v_pk_add_f32 v[68:69], v[50:51], v[68:69]
	v_lshlrev_b32_e32 v50, 16, v71
	v_and_b32_e32 v51, 0xffff0000, v71
	v_pk_add_f32 v[54:55], v[54:55], v[74:75]
	v_pk_add_f32 v[70:71], v[52:53], v[50:51]
	v_cvt_pk_bf16_f32 v50, v54, v55
	v_cvt_pk_bf16_f32 v51, v56, v57
	v_cvt_pk_bf16_f32 v52, v68, v69
	v_cvt_pk_bf16_f32 v53, v70, v71
	global_store_dwordx4 v[72:73], v[50:53], off offset:256 nt
	s_nop 1
	v_pk_mul_f32 v[50:51], v[54:55], v[54:55]
	v_pk_mul_f32 v[52:53], v[56:57], v[56:57]
	v_add_f32_e32 v50, v50, v51
	v_add_f32_e32 v51, v64, v65
	v_add_f32_e32 v50, v52, v50
	v_add_f32_e32 v51, v62, v51
	v_pk_mul_f32 v[54:55], v[68:69], v[68:69]
	v_add_f32_e32 v50, v53, v50
	v_add_f32_e32 v51, v63, v51
	v_add_f32_e32 v50, v54, v50
	v_add_f32_e32 v51, v60, v51
	v_pk_mul_f32 v[56:57], v[70:71], v[70:71]
	v_add_f32_e32 v50, v55, v50
	v_add_f32_e32 v51, v61, v51
	v_add_f32_e32 v50, v56, v50
	v_add_f32_e32 v51, v58, v51
	v_add_f32_e32 v50, v57, v50
	v_add_f32_e32 v51, v59, v51
	v_add_f32_e32 v50, v51, v50
	ds_bpermute_b32 v51, v161, v50
	s_waitcnt lgkmcnt(0)
	v_add_f32_e32 v50, v50, v51
	ds_bpermute_b32 v51, v160, v50
	s_and_saveexec_b64 s[28:29], s[38:39]
	s_cbranch_execz .LBB0_423
	v_readlane_b32 s52, v252, 41
	v_lshlrev_b64 v[52:53], 6, v[66:67]
	v_readlane_b32 s53, v252, 42
	s_waitcnt lgkmcnt(0)
	v_add_f32_e32 v50, v50, v51
	v_lshl_add_u64 v[52:53], s[52:53], 0, v[52:53]
	v_lshl_add_u64 v[52:53], s[42:43], 2, v[52:53]
	s_lshl_b32 s52, s92, 2
	s_mov_b32 s53, s95
	v_lshl_add_u64 v[52:53], v[52:53], 0, s[52:53]
	global_store_dword v[52:53], v50, off nt
.LBB0_423:
	s_or_b64 exec, exec, s[28:29]
	s_mov_b64 s[28:29], 0x90
	s_waitcnt lgkmcnt(0)
	v_lshl_add_u64 v[50:51], v[156:157], 0, s[28:29]
	v_readlane_b32 s28, v253, 40
	v_lshlrev_b64 v[52:53], 11, v[50:51]
	v_readlane_b32 s29, v253, 41
	s_nop 1
	v_lshl_add_u64 v[52:53], s[28:29], 0, v[52:53]
	v_lshl_add_u64 v[52:53], s[2:3], 1, v[52:53]
	v_lshl_add_u64 v[52:53], v[52:53], 0, s[94:95]
	v_lshl_add_u64 v[56:57], v[52:53], 0, v[0:1]
	global_load_dwordx4 v[52:55], v[56:57], off
	s_waitcnt vmcnt(0)
	v_lshlrev_b32_e32 v58, 16, v52
	v_and_b32_e32 v59, 0xffff0000, v52
	v_lshlrev_b32_e32 v52, 16, v53
	v_and_b32_e32 v53, 0xffff0000, v53
	v_pk_add_f32 v[52:53], v[48:49], v[52:53]
	v_lshlrev_b32_e32 v48, 16, v54
	v_and_b32_e32 v49, 0xffff0000, v54
	v_pk_add_f32 v[46:47], v[46:47], v[58:59]
	v_pk_add_f32 v[58:59], v[42:43], v[48:49]
	v_lshlrev_b32_e32 v42, 16, v55
	v_and_b32_e32 v43, 0xffff0000, v55
	v_pk_add_f32 v[54:55], v[44:45], v[42:43]
	v_cvt_pk_bf16_f32 v42, v46, v47
	v_cvt_pk_bf16_f32 v43, v52, v53
	v_cvt_pk_bf16_f32 v44, v58, v59
	v_cvt_pk_bf16_f32 v45, v54, v55
	global_store_dwordx4 v[56:57], v[42:45], off nt
	v_pk_mul_f32 v[48:49], v[46:47], v[46:47]
	v_pk_mul_f32 v[46:47], v[52:53], v[52:53]
	v_pk_mul_f32 v[42:43], v[54:55], v[54:55]
	global_load_dwordx4 v[52:55], v[56:57], off offset:256
	v_pk_mul_f32 v[44:45], v[58:59], v[58:59]
	s_waitcnt vmcnt(0)
	v_lshlrev_b32_e32 v58, 16, v52
	v_and_b32_e32 v59, 0xffff0000, v52
	v_lshlrev_b32_e32 v52, 16, v53
	v_and_b32_e32 v53, 0xffff0000, v53
	v_pk_add_f32 v[40:41], v[40:41], v[52:53]
	v_lshlrev_b32_e32 v52, 16, v54
	v_and_b32_e32 v53, 0xffff0000, v54
	v_pk_add_f32 v[52:53], v[34:35], v[52:53]
	v_lshlrev_b32_e32 v34, 16, v55
	v_and_b32_e32 v35, 0xffff0000, v55
	v_pk_add_f32 v[38:39], v[38:39], v[58:59]
	v_pk_add_f32 v[54:55], v[36:37], v[34:35]
	v_cvt_pk_bf16_f32 v34, v38, v39
	v_cvt_pk_bf16_f32 v35, v40, v41
	v_cvt_pk_bf16_f32 v36, v52, v53
	v_cvt_pk_bf16_f32 v37, v54, v55
	global_store_dwordx4 v[56:57], v[34:37], off offset:256 nt
	s_nop 1
	v_pk_mul_f32 v[34:35], v[38:39], v[38:39]
	v_pk_mul_f32 v[36:37], v[40:41], v[40:41]
	v_add_f32_e32 v34, v34, v35
	v_add_f32_e32 v35, v48, v49
	v_add_f32_e32 v34, v36, v34
	v_add_f32_e32 v35, v46, v35
	v_pk_mul_f32 v[38:39], v[52:53], v[52:53]
	v_add_f32_e32 v34, v37, v34
	v_add_f32_e32 v35, v47, v35
	v_add_f32_e32 v34, v38, v34
	v_add_f32_e32 v35, v44, v35
	v_pk_mul_f32 v[40:41], v[54:55], v[54:55]
	v_add_f32_e32 v34, v39, v34
	v_add_f32_e32 v35, v45, v35
	v_add_f32_e32 v34, v40, v34
	v_add_f32_e32 v35, v42, v35
	v_add_f32_e32 v34, v41, v34
	v_add_f32_e32 v35, v43, v35
	v_add_f32_e32 v34, v35, v34
	ds_bpermute_b32 v35, v161, v34
	s_waitcnt lgkmcnt(0)
	v_add_f32_e32 v34, v34, v35
	ds_bpermute_b32 v35, v160, v34
	s_and_saveexec_b64 s[28:29], s[38:39]
	s_cbranch_execz .LBB0_425
	v_readlane_b32 s52, v252, 41
	v_lshlrev_b64 v[36:37], 6, v[50:51]
	v_readlane_b32 s53, v252, 42
	s_waitcnt lgkmcnt(0)
	v_add_f32_e32 v34, v34, v35
	v_lshl_add_u64 v[36:37], s[52:53], 0, v[36:37]
	v_lshl_add_u64 v[36:37], s[42:43], 2, v[36:37]
	s_lshl_b32 s52, s92, 2
	s_mov_b32 s53, s95
	v_lshl_add_u64 v[36:37], v[36:37], 0, s[52:53]
	global_store_dword v[36:37], v34, off nt
.LBB0_425:
	s_or_b64 exec, exec, s[28:29]
	s_mov_b64 s[28:29], 0xa0
	s_waitcnt lgkmcnt(0)
	v_lshl_add_u64 v[34:35], v[156:157], 0, s[28:29]
	v_readlane_b32 s28, v253, 40
	v_lshlrev_b64 v[36:37], 11, v[34:35]
	v_readlane_b32 s29, v253, 41
	s_nop 1
	v_lshl_add_u64 v[36:37], s[28:29], 0, v[36:37]
	v_lshl_add_u64 v[36:37], s[2:3], 1, v[36:37]
	v_lshl_add_u64 v[36:37], v[36:37], 0, s[94:95]
	v_lshl_add_u64 v[40:41], v[36:37], 0, v[0:1]
	global_load_dwordx4 v[36:39], v[40:41], off
	s_waitcnt vmcnt(0)
	v_lshlrev_b32_e32 v42, 16, v36
	v_and_b32_e32 v43, 0xffff0000, v36
	v_lshlrev_b32_e32 v36, 16, v37
	v_and_b32_e32 v37, 0xffff0000, v37
	v_pk_add_f32 v[36:37], v[32:33], v[36:37]
	v_lshlrev_b32_e32 v32, 16, v38
	v_and_b32_e32 v33, 0xffff0000, v38
	v_pk_add_f32 v[30:31], v[30:31], v[42:43]
	v_pk_add_f32 v[42:43], v[26:27], v[32:33]
	v_lshlrev_b32_e32 v26, 16, v39
	v_and_b32_e32 v27, 0xffff0000, v39
	v_pk_add_f32 v[38:39], v[28:29], v[26:27]
	v_cvt_pk_bf16_f32 v26, v30, v31
	v_cvt_pk_bf16_f32 v27, v36, v37
	v_cvt_pk_bf16_f32 v28, v42, v43
	v_cvt_pk_bf16_f32 v29, v38, v39
	global_store_dwordx4 v[40:41], v[26:29], off nt
	v_pk_mul_f32 v[32:33], v[30:31], v[30:31]
	v_pk_mul_f32 v[30:31], v[36:37], v[36:37]
	v_pk_mul_f32 v[26:27], v[38:39], v[38:39]
	global_load_dwordx4 v[36:39], v[40:41], off offset:256
	v_pk_mul_f32 v[28:29], v[42:43], v[42:43]
	s_waitcnt vmcnt(0)
	v_lshlrev_b32_e32 v42, 16, v36
	v_and_b32_e32 v43, 0xffff0000, v36
	v_lshlrev_b32_e32 v36, 16, v37
	v_and_b32_e32 v37, 0xffff0000, v37
	v_pk_add_f32 v[24:25], v[24:25], v[36:37]
	v_lshlrev_b32_e32 v36, 16, v38
	v_and_b32_e32 v37, 0xffff0000, v38
	v_pk_add_f32 v[36:37], v[18:19], v[36:37]
	v_lshlrev_b32_e32 v18, 16, v39
	v_and_b32_e32 v19, 0xffff0000, v39
	v_pk_add_f32 v[22:23], v[22:23], v[42:43]
	v_pk_add_f32 v[38:39], v[20:21], v[18:19]
	v_cvt_pk_bf16_f32 v18, v22, v23
	v_cvt_pk_bf16_f32 v19, v24, v25
	v_cvt_pk_bf16_f32 v20, v36, v37
	v_cvt_pk_bf16_f32 v21, v38, v39
	global_store_dwordx4 v[40:41], v[18:21], off offset:256 nt
	s_nop 1
	v_pk_mul_f32 v[18:19], v[22:23], v[22:23]
	v_pk_mul_f32 v[20:21], v[24:25], v[24:25]
	v_add_f32_e32 v18, v18, v19
	v_add_f32_e32 v19, v32, v33
	v_add_f32_e32 v18, v20, v18
	v_add_f32_e32 v19, v30, v19
	v_pk_mul_f32 v[22:23], v[36:37], v[36:37]
	v_add_f32_e32 v18, v21, v18
	v_add_f32_e32 v19, v31, v19
	v_add_f32_e32 v18, v22, v18
	v_add_f32_e32 v19, v28, v19
	v_pk_mul_f32 v[24:25], v[38:39], v[38:39]
	v_add_f32_e32 v18, v23, v18
	v_add_f32_e32 v19, v29, v19
	v_add_f32_e32 v18, v24, v18
	v_add_f32_e32 v19, v26, v19
	v_add_f32_e32 v18, v25, v18
	v_add_f32_e32 v19, v27, v19
	v_add_f32_e32 v18, v19, v18
	ds_bpermute_b32 v19, v161, v18
	s_waitcnt lgkmcnt(0)
	v_add_f32_e32 v18, v18, v19
	ds_bpermute_b32 v19, v160, v18
	s_and_saveexec_b64 s[28:29], s[38:39]
	s_cbranch_execz .LBB0_427
	v_readlane_b32 s52, v252, 41
	v_lshlrev_b64 v[20:21], 6, v[34:35]
	v_readlane_b32 s53, v252, 42
	s_waitcnt lgkmcnt(0)
	v_add_f32_e32 v18, v18, v19
	v_lshl_add_u64 v[20:21], s[52:53], 0, v[20:21]
	v_lshl_add_u64 v[20:21], s[42:43], 2, v[20:21]
	s_lshl_b32 s52, s92, 2
	s_mov_b32 s53, s95
	v_lshl_add_u64 v[20:21], v[20:21], 0, s[52:53]
	global_store_dword v[20:21], v18, off nt
.LBB0_427:
	s_or_b64 exec, exec, s[28:29]
	s_mov_b64 s[28:29], 0xb0
	s_waitcnt lgkmcnt(0)
	v_lshl_add_u64 v[18:19], v[156:157], 0, s[28:29]
	v_readlane_b32 s28, v253, 40
	v_lshlrev_b64 v[20:21], 11, v[18:19]
	v_readlane_b32 s29, v253, 41
	s_nop 1
	v_lshl_add_u64 v[20:21], s[28:29], 0, v[20:21]
	v_lshl_add_u64 v[20:21], s[2:3], 1, v[20:21]
	v_lshl_add_u64 v[20:21], v[20:21], 0, s[94:95]
	v_lshl_add_u64 v[24:25], v[20:21], 0, v[0:1]
	global_load_dwordx4 v[20:23], v[24:25], off
	s_waitcnt vmcnt(0)
	v_lshlrev_b32_e32 v26, 16, v20
	v_and_b32_e32 v27, 0xffff0000, v20
	v_lshlrev_b32_e32 v20, 16, v21
	v_and_b32_e32 v21, 0xffff0000, v21
	v_pk_add_f32 v[20:21], v[16:17], v[20:21]
	v_lshlrev_b32_e32 v16, 16, v22
	v_and_b32_e32 v17, 0xffff0000, v22
	v_pk_add_f32 v[14:15], v[14:15], v[26:27]
	v_pk_add_f32 v[26:27], v[10:11], v[16:17]
	v_lshlrev_b32_e32 v10, 16, v23
	v_and_b32_e32 v11, 0xffff0000, v23
	v_pk_add_f32 v[22:23], v[12:13], v[10:11]
	v_cvt_pk_bf16_f32 v10, v14, v15
	v_cvt_pk_bf16_f32 v11, v20, v21
	v_cvt_pk_bf16_f32 v12, v26, v27
	v_cvt_pk_bf16_f32 v13, v22, v23
	global_store_dwordx4 v[24:25], v[10:13], off nt
	v_pk_mul_f32 v[16:17], v[14:15], v[14:15]
	v_pk_mul_f32 v[14:15], v[20:21], v[20:21]
	v_pk_mul_f32 v[10:11], v[22:23], v[22:23]
	global_load_dwordx4 v[20:23], v[24:25], off offset:256
	v_pk_mul_f32 v[12:13], v[26:27], v[26:27]
	s_waitcnt vmcnt(0)
	v_lshlrev_b32_e32 v26, 16, v20
	v_and_b32_e32 v27, 0xffff0000, v20
	v_lshlrev_b32_e32 v20, 16, v21
	v_and_b32_e32 v21, 0xffff0000, v21
	v_pk_add_f32 v[8:9], v[8:9], v[20:21]
	v_lshlrev_b32_e32 v20, 16, v22
	v_and_b32_e32 v21, 0xffff0000, v22
	v_pk_add_f32 v[20:21], v[2:3], v[20:21]
	v_lshlrev_b32_e32 v2, 16, v23
	v_and_b32_e32 v3, 0xffff0000, v23
	v_pk_add_f32 v[6:7], v[6:7], v[26:27]
	v_pk_add_f32 v[22:23], v[4:5], v[2:3]
	v_cvt_pk_bf16_f32 v2, v6, v7
	v_cvt_pk_bf16_f32 v3, v8, v9
	v_cvt_pk_bf16_f32 v4, v20, v21
	v_cvt_pk_bf16_f32 v5, v22, v23
	global_store_dwordx4 v[24:25], v[2:5], off offset:256 nt
	s_nop 1
	v_pk_mul_f32 v[2:3], v[6:7], v[6:7]
	v_pk_mul_f32 v[4:5], v[8:9], v[8:9]
	v_add_f32_e32 v0, v2, v3
	v_add_f32_e32 v2, v16, v17
	v_add_f32_e32 v0, v4, v0
	v_add_f32_e32 v2, v14, v2
	v_pk_mul_f32 v[6:7], v[20:21], v[20:21]
	v_add_f32_e32 v0, v5, v0
	v_add_f32_e32 v2, v15, v2
	v_add_f32_e32 v0, v6, v0
	v_add_f32_e32 v2, v12, v2
	v_pk_mul_f32 v[8:9], v[22:23], v[22:23]
	v_add_f32_e32 v0, v7, v0
	v_add_f32_e32 v2, v13, v2
	v_add_f32_e32 v0, v8, v0
	v_add_f32_e32 v2, v10, v2
	v_add_f32_e32 v0, v9, v0
	v_add_f32_e32 v2, v11, v2
	v_add_f32_e32 v0, v2, v0
	ds_bpermute_b32 v2, v161, v0
	s_waitcnt lgkmcnt(0)
	v_add_f32_e32 v0, v0, v2
	ds_bpermute_b32 v2, v160, v0
	s_and_saveexec_b64 s[2:3], s[38:39]
	s_cbranch_execz .LBB0_429
	v_readlane_b32 s28, v252, 41
	v_lshlrev_b64 v[4:5], 6, v[18:19]
	v_readlane_b32 s29, v252, 42
	s_lshl_b32 s94, s92, 2
	s_waitcnt lgkmcnt(0)
	v_add_f32_e32 v0, v0, v2
	v_lshl_add_u64 v[4:5], s[28:29], 0, v[4:5]
	v_lshl_add_u64 v[4:5], s[42:43], 2, v[4:5]
	v_lshl_add_u64 v[4:5], v[4:5], 0, s[94:95]
	global_store_dword v[4:5], v0, off nt

.LBB0_476:
	s_ashr_i32 s3, s2, 31
	s_lshl_b64 s[2:3], s[2:3], 8
	v_lshl_add_u64 v[156:157], s[2:3], 0, v[150:151]
	v_readlane_b32 s28, v253, 40
	s_lshl_b32 s2, s37, 8
	v_cmp_lt_i32_e32 vcc, v192, v187
	v_lshlrev_b64 v[136:137], 11, v[156:157]
	v_readlane_b32 s29, v253, 41
	s_ashr_i32 s3, s2, 31
	v_cndmask_b32_e32 v0, v186, v192, vcc
	v_cmp_lt_i32_e32 vcc, v193, v187
	v_lshl_add_u64 v[136:137], s[28:29], 0, v[136:137]
	v_readlane_b32 s28, v254, 63
	v_lshlrev_b32_e32 v161, 2, v0
	v_cndmask_b32_e32 v0, v186, v193, vcc
	v_lshl_add_u64 v[136:137], s[2:3], 1, v[136:137]
	s_lshl_b32 s94, s28, 1
	v_lshlrev_b32_e32 v160, 2, v0
	v_lshl_add_u64 v[136:137], v[136:137], 0, s[94:95]
	v_lshlrev_b32_e32 v0, 1, v148
	v_lshl_add_u64 v[158:159], v[136:137], 0, v[0:1]
	global_load_dwordx4 v[162:165], v[158:159], off
	s_lshl_b32 s52, s37, 2
	s_ashr_i32 s53, s52, 31
	s_waitcnt vmcnt(0)
	v_lshlrev_b32_e32 v136, 16, v162
	v_and_b32_e32 v137, 0xffff0000, v162
	v_pk_add_f32 v[126:127], v[126:127], v[136:137]
	v_lshlrev_b32_e32 v136, 16, v163
	v_and_b32_e32 v137, 0xffff0000, v163
	v_pk_add_f32 v[136:137], v[128:129], v[136:137]
	v_lshlrev_b32_e32 v128, 16, v164
	v_and_b32_e32 v129, 0xffff0000, v164
	v_pk_add_f32 v[138:139], v[122:123], v[128:129]
	v_lshlrev_b32_e32 v122, 16, v165
	v_and_b32_e32 v123, 0xffff0000, v165
	v_pk_add_f32 v[162:163], v[124:125], v[122:123]
	v_cvt_pk_bf16_f32 v122, v126, v127
	v_cvt_pk_bf16_f32 v123, v136, v137
	v_cvt_pk_bf16_f32 v124, v138, v139
	v_cvt_pk_bf16_f32 v125, v162, v163
	global_store_dwordx4 v[158:159], v[122:125], off nt
	v_pk_mul_f32 v[128:129], v[126:127], v[126:127]
	v_pk_mul_f32 v[126:127], v[136:137], v[136:137]
	v_pk_mul_f32 v[122:123], v[162:163], v[162:163]
	global_load_dwordx4 v[162:165], v[158:159], off offset:256
	v_pk_mul_f32 v[124:125], v[138:139], v[138:139]
	s_waitcnt vmcnt(0)
	v_lshlrev_b32_e32 v136, 16, v162
	v_and_b32_e32 v137, 0xffff0000, v162
	v_pk_add_f32 v[118:119], v[118:119], v[136:137]
	v_lshlrev_b32_e32 v136, 16, v163
	v_and_b32_e32 v137, 0xffff0000, v163
	v_pk_add_f32 v[120:121], v[120:121], v[136:137]
	v_lshlrev_b32_e32 v136, 16, v164
	v_and_b32_e32 v137, 0xffff0000, v164
	v_pk_add_f32 v[136:137], v[114:115], v[136:137]
	v_lshlrev_b32_e32 v114, 16, v165
	v_and_b32_e32 v115, 0xffff0000, v165
	v_pk_add_f32 v[138:139], v[116:117], v[114:115]
	v_cvt_pk_bf16_f32 v114, v118, v119
	v_cvt_pk_bf16_f32 v115, v120, v121
	v_cvt_pk_bf16_f32 v116, v136, v137
	v_cvt_pk_bf16_f32 v117, v138, v139
	global_store_dwordx4 v[158:159], v[114:117], off offset:256 nt
	s_nop 1
	v_pk_mul_f32 v[114:115], v[118:119], v[118:119]
	v_pk_mul_f32 v[116:117], v[120:121], v[120:121]
	v_add_f32_e32 v114, v114, v115
	v_add_f32_e32 v115, v128, v129
	v_add_f32_e32 v114, v116, v114
	v_add_f32_e32 v115, v126, v115
	v_pk_mul_f32 v[118:119], v[136:137], v[136:137]
	v_add_f32_e32 v114, v117, v114
	v_add_f32_e32 v115, v127, v115
	v_add_f32_e32 v114, v118, v114
	v_add_f32_e32 v115, v124, v115
	v_pk_mul_f32 v[120:121], v[138:139], v[138:139]
	v_add_f32_e32 v114, v119, v114
	v_add_f32_e32 v115, v125, v115
	v_add_f32_e32 v114, v120, v114
	v_add_f32_e32 v115, v122, v115
	v_add_f32_e32 v114, v121, v114
	v_add_f32_e32 v115, v123, v115
	v_add_f32_e32 v114, v115, v114
	ds_bpermute_b32 v115, v161, v114
	s_waitcnt lgkmcnt(0)
	v_add_f32_e32 v114, v114, v115
	ds_bpermute_b32 v115, v160, v114
	s_and_saveexec_b64 s[28:29], s[38:39]
	v_readlane_b32 s82, v254, 31
	v_readlane_b32 s83, v254, 32
	s_cbranch_execz .LBB0_478
	v_readlane_b32 s58, v252, 43
	v_lshlrev_b64 v[116:117], 6, v[156:157]
	v_readlane_b32 s59, v252, 44
	s_waitcnt lgkmcnt(0)
	v_add_f32_e32 v114, v114, v115
	v_lshl_add_u64 v[116:117], s[58:59], 0, v[116:117]
	v_lshl_add_u64 v[116:117], s[52:53], 2, v[116:117]
	s_lshl_b32 s58, s91, 2
	s_mov_b32 s59, s95
	v_lshl_add_u64 v[116:117], v[116:117], 0, s[58:59]
	global_store_dword v[116:117], v114, off nt
.LBB0_478:
	s_or_b64 exec, exec, s[28:29]
	v_or_b32_e32 v114, 16, v156
	s_waitcnt lgkmcnt(0)
	v_mov_b32_e32 v115, v157
	v_readlane_b32 s28, v253, 40
	v_lshlrev_b64 v[116:117], 11, v[114:115]
	v_readlane_b32 s29, v253, 41
	s_nop 1
	v_lshl_add_u64 v[116:117], s[28:29], 0, v[116:117]
	v_lshl_add_u64 v[116:117], s[2:3], 1, v[116:117]
	v_lshl_add_u64 v[116:117], v[116:117], 0, s[94:95]
	v_lshl_add_u64 v[120:121], v[116:117], 0, v[0:1]
	global_load_dwordx4 v[116:119], v[120:121], off
	s_waitcnt vmcnt(0)
	v_lshlrev_b32_e32 v122, 16, v116
	v_and_b32_e32 v123, 0xffff0000, v116
	v_lshlrev_b32_e32 v116, 16, v117
	v_and_b32_e32 v117, 0xffff0000, v117
	v_pk_add_f32 v[116:117], v[112:113], v[116:117]
	v_lshlrev_b32_e32 v112, 16, v118
	v_and_b32_e32 v113, 0xffff0000, v118
	v_pk_add_f32 v[110:111], v[110:111], v[122:123]
	v_pk_add_f32 v[122:123], v[106:107], v[112:113]
	v_lshlrev_b32_e32 v106, 16, v119
	v_and_b32_e32 v107, 0xffff0000, v119
	v_pk_add_f32 v[118:119], v[108:109], v[106:107]
	v_cvt_pk_bf16_f32 v106, v110, v111
	v_cvt_pk_bf16_f32 v107, v116, v117
	v_cvt_pk_bf16_f32 v108, v122, v123
	v_cvt_pk_bf16_f32 v109, v118, v119
	global_store_dwordx4 v[120:121], v[106:109], off nt
	v_pk_mul_f32 v[112:113], v[110:111], v[110:111]
	v_pk_mul_f32 v[110:111], v[116:117], v[116:117]
	v_pk_mul_f32 v[106:107], v[118:119], v[118:119]
	global_load_dwordx4 v[116:119], v[120:121], off offset:256
	v_pk_mul_f32 v[108:109], v[122:123], v[122:123]
	s_waitcnt vmcnt(0)
	v_lshlrev_b32_e32 v122, 16, v116
	v_and_b32_e32 v123, 0xffff0000, v116
	v_lshlrev_b32_e32 v116, 16, v117
	v_and_b32_e32 v117, 0xffff0000, v117
	v_pk_add_f32 v[104:105], v[104:105], v[116:117]
	v_lshlrev_b32_e32 v116, 16, v118
	v_and_b32_e32 v117, 0xffff0000, v118
	v_pk_add_f32 v[116:117], v[98:99], v[116:117]
	v_lshlrev_b32_e32 v98, 16, v119
	v_and_b32_e32 v99, 0xffff0000, v119
	v_pk_add_f32 v[102:103], v[102:103], v[122:123]
	v_pk_add_f32 v[118:119], v[100:101], v[98:99]
	v_cvt_pk_bf16_f32 v98, v102, v103
	v_cvt_pk_bf16_f32 v99, v104, v105
	v_cvt_pk_bf16_f32 v100, v116, v117
	v_cvt_pk_bf16_f32 v101, v118, v119
	global_store_dwordx4 v[120:121], v[98:101], off offset:256 nt
	s_nop 1
	v_pk_mul_f32 v[98:99], v[102:103], v[102:103]
	v_pk_mul_f32 v[100:101], v[104:105], v[104:105]
	v_add_f32_e32 v98, v98, v99
	v_add_f32_e32 v99, v112, v113
	v_add_f32_e32 v98, v100, v98
	v_add_f32_e32 v99, v110, v99
	v_pk_mul_f32 v[102:103], v[116:117], v[116:117]
	v_add_f32_e32 v98, v101, v98
	v_add_f32_e32 v99, v111, v99
	v_add_f32_e32 v98, v102, v98
	v_add_f32_e32 v99, v108, v99
	v_pk_mul_f32 v[104:105], v[118:119], v[118:119]
	v_add_f32_e32 v98, v103, v98
	v_add_f32_e32 v99, v109, v99
	v_add_f32_e32 v98, v104, v98
	v_add_f32_e32 v99, v106, v99
	v_add_f32_e32 v98, v105, v98
	v_add_f32_e32 v99, v107, v99
	v_add_f32_e32 v98, v99, v98
	ds_bpermute_b32 v99, v161, v98
	s_waitcnt lgkmcnt(0)
	v_add_f32_e32 v98, v98, v99
	ds_bpermute_b32 v99, v160, v98
	s_and_saveexec_b64 s[28:29], s[38:39]
	s_cbranch_execz .LBB0_480
	v_readlane_b32 s58, v252, 43
	v_lshlrev_b64 v[100:101], 6, v[114:115]
	v_readlane_b32 s59, v252, 44
	s_waitcnt lgkmcnt(0)
	v_add_f32_e32 v98, v98, v99
	v_lshl_add_u64 v[100:101], s[58:59], 0, v[100:101]
	v_lshl_add_u64 v[100:101], s[52:53], 2, v[100:101]
	s_lshl_b32 s58, s91, 2
	s_mov_b32 s59, s95
	v_lshl_add_u64 v[100:101], v[100:101], 0, s[58:59]
	global_store_dword v[100:101], v98, off nt
.LBB0_480:
	s_or_b64 exec, exec, s[28:29]
	v_or_b32_e32 v98, 32, v156
	s_waitcnt lgkmcnt(0)
	v_mov_b32_e32 v99, v157
	v_readlane_b32 s28, v253, 40
	v_lshlrev_b64 v[100:101], 11, v[98:99]
	v_readlane_b32 s29, v253, 41
	s_nop 1
	v_lshl_add_u64 v[100:101], s[28:29], 0, v[100:101]
	v_lshl_add_u64 v[100:101], s[2:3], 1, v[100:101]
	v_lshl_add_u64 v[100:101], v[100:101], 0, s[94:95]
	v_lshl_add_u64 v[104:105], v[100:101], 0, v[0:1]
	global_load_dwordx4 v[100:103], v[104:105], off
	s_waitcnt vmcnt(0)
	v_lshlrev_b32_e32 v106, 16, v100
	v_and_b32_e32 v107, 0xffff0000, v100
	v_lshlrev_b32_e32 v100, 16, v101
	v_and_b32_e32 v101, 0xffff0000, v101
	v_pk_add_f32 v[100:101], v[96:97], v[100:101]
	v_lshlrev_b32_e32 v96, 16, v102
	v_and_b32_e32 v97, 0xffff0000, v102
	v_pk_add_f32 v[94:95], v[94:95], v[106:107]
	v_pk_add_f32 v[106:107], v[90:91], v[96:97]
	v_lshlrev_b32_e32 v90, 16, v103
	v_and_b32_e32 v91, 0xffff0000, v103
	v_pk_add_f32 v[102:103], v[92:93], v[90:91]
	v_cvt_pk_bf16_f32 v90, v94, v95
	v_cvt_pk_bf16_f32 v91, v100, v101
	v_cvt_pk_bf16_f32 v92, v106, v107
	v_cvt_pk_bf16_f32 v93, v102, v103
	global_store_dwordx4 v[104:105], v[90:93], off nt
	v_pk_mul_f32 v[96:97], v[94:95], v[94:95]
	v_pk_mul_f32 v[94:95], v[100:101], v[100:101]
	v_pk_mul_f32 v[90:91], v[102:103], v[102:103]
	global_load_dwordx4 v[100:103], v[104:105], off offset:256
	v_pk_mul_f32 v[92:93], v[106:107], v[106:107]
	s_waitcnt vmcnt(0)
	v_lshlrev_b32_e32 v106, 16, v100
	v_and_b32_e32 v107, 0xffff0000, v100
	v_lshlrev_b32_e32 v100, 16, v101
	v_and_b32_e32 v101, 0xffff0000, v101
	v_pk_add_f32 v[88:89], v[88:89], v[100:101]
	v_lshlrev_b32_e32 v100, 16, v102
	v_and_b32_e32 v101, 0xffff0000, v102
	v_pk_add_f32 v[100:101], v[82:83], v[100:101]
	v_lshlrev_b32_e32 v82, 16, v103
	v_and_b32_e32 v83, 0xffff0000, v103
	v_pk_add_f32 v[86:87], v[86:87], v[106:107]
	v_pk_add_f32 v[102:103], v[84:85], v[82:83]
	v_cvt_pk_bf16_f32 v82, v86, v87
	v_cvt_pk_bf16_f32 v83, v88, v89
	v_cvt_pk_bf16_f32 v84, v100, v101
	v_cvt_pk_bf16_f32 v85, v102, v103
	global_store_dwordx4 v[104:105], v[82:85], off offset:256 nt
	s_nop 1
	v_pk_mul_f32 v[82:83], v[86:87], v[86:87]
	v_pk_mul_f32 v[84:85], v[88:89], v[88:89]
	v_add_f32_e32 v82, v82, v83
	v_add_f32_e32 v83, v96, v97
	v_add_f32_e32 v82, v84, v82
	v_add_f32_e32 v83, v94, v83
	v_pk_mul_f32 v[86:87], v[100:101], v[100:101]
	v_add_f32_e32 v82, v85, v82
	v_add_f32_e32 v83, v95, v83
	v_add_f32_e32 v82, v86, v82
	v_add_f32_e32 v83, v92, v83
	v_pk_mul_f32 v[88:89], v[102:103], v[102:103]
	v_add_f32_e32 v82, v87, v82
	v_add_f32_e32 v83, v93, v83
	v_add_f32_e32 v82, v88, v82
	v_add_f32_e32 v83, v90, v83
	v_add_f32_e32 v82, v89, v82
	v_add_f32_e32 v83, v91, v83
	v_add_f32_e32 v82, v83, v82
	ds_bpermute_b32 v83, v161, v82
	s_waitcnt lgkmcnt(0)
	v_add_f32_e32 v82, v82, v83
	ds_bpermute_b32 v83, v160, v82
	s_and_saveexec_b64 s[28:29], s[38:39]
	v_readlane_b32 s80, v254, 33
	v_readlane_b32 s81, v254, 34
	s_cbranch_execz .LBB0_482
	v_readlane_b32 s58, v252, 43
	v_lshlrev_b64 v[84:85], 6, v[98:99]
	v_readlane_b32 s59, v252, 44
	s_waitcnt lgkmcnt(0)
	v_add_f32_e32 v82, v82, v83
	v_lshl_add_u64 v[84:85], s[58:59], 0, v[84:85]
	v_lshl_add_u64 v[84:85], s[52:53], 2, v[84:85]
	s_lshl_b32 s58, s91, 2
	s_mov_b32 s59, s95
	v_lshl_add_u64 v[84:85], v[84:85], 0, s[58:59]
	global_store_dword v[84:85], v82, off nt
.LBB0_482:
	s_or_b64 exec, exec, s[28:29]
	v_or_b32_e32 v82, 48, v156
	s_waitcnt lgkmcnt(0)
	v_mov_b32_e32 v83, v157
	v_readlane_b32 s28, v253, 40
	v_lshlrev_b64 v[84:85], 11, v[82:83]
	v_readlane_b32 s29, v253, 41
	s_nop 1
	v_lshl_add_u64 v[84:85], s[28:29], 0, v[84:85]
	v_lshl_add_u64 v[84:85], s[2:3], 1, v[84:85]
	v_lshl_add_u64 v[84:85], v[84:85], 0, s[94:95]
	v_lshl_add_u64 v[88:89], v[84:85], 0, v[0:1]
	global_load_dwordx4 v[84:87], v[88:89], off
	s_waitcnt vmcnt(0)
	v_lshlrev_b32_e32 v90, 16, v84
	v_and_b32_e32 v91, 0xffff0000, v84
	v_lshlrev_b32_e32 v84, 16, v85
	v_and_b32_e32 v85, 0xffff0000, v85
	v_pk_add_f32 v[84:85], v[80:81], v[84:85]
	v_lshlrev_b32_e32 v80, 16, v86
	v_and_b32_e32 v81, 0xffff0000, v86
	v_pk_add_f32 v[78:79], v[78:79], v[90:91]
	v_pk_add_f32 v[90:91], v[74:75], v[80:81]
	v_lshlrev_b32_e32 v74, 16, v87
	v_and_b32_e32 v75, 0xffff0000, v87
	v_pk_add_f32 v[86:87], v[76:77], v[74:75]
	v_cvt_pk_bf16_f32 v74, v78, v79
	v_cvt_pk_bf16_f32 v75, v84, v85
	v_cvt_pk_bf16_f32 v76, v90, v91
	v_cvt_pk_bf16_f32 v77, v86, v87
	global_store_dwordx4 v[88:89], v[74:77], off nt
	v_pk_mul_f32 v[80:81], v[78:79], v[78:79]
	v_pk_mul_f32 v[78:79], v[84:85], v[84:85]
	v_pk_mul_f32 v[74:75], v[86:87], v[86:87]
	global_load_dwordx4 v[84:87], v[88:89], off offset:256
	v_pk_mul_f32 v[76:77], v[90:91], v[90:91]
	s_waitcnt vmcnt(0)
	v_lshlrev_b32_e32 v90, 16, v84
	v_and_b32_e32 v91, 0xffff0000, v84
	v_lshlrev_b32_e32 v84, 16, v85
	v_and_b32_e32 v85, 0xffff0000, v85
	v_pk_add_f32 v[72:73], v[72:73], v[84:85]
	v_lshlrev_b32_e32 v84, 16, v86
	v_and_b32_e32 v85, 0xffff0000, v86
	v_pk_add_f32 v[84:85], v[66:67], v[84:85]
	v_lshlrev_b32_e32 v66, 16, v87
	v_and_b32_e32 v67, 0xffff0000, v87
	v_pk_add_f32 v[70:71], v[70:71], v[90:91]
	v_pk_add_f32 v[86:87], v[68:69], v[66:67]
	v_cvt_pk_bf16_f32 v66, v70, v71
	v_cvt_pk_bf16_f32 v67, v72, v73
	v_cvt_pk_bf16_f32 v68, v84, v85
	v_cvt_pk_bf16_f32 v69, v86, v87
	global_store_dwordx4 v[88:89], v[66:69], off offset:256 nt
	s_nop 1
	v_pk_mul_f32 v[66:67], v[70:71], v[70:71]
	v_pk_mul_f32 v[68:69], v[72:73], v[72:73]
	v_add_f32_e32 v66, v66, v67
	v_add_f32_e32 v67, v80, v81
	v_add_f32_e32 v66, v68, v66
	v_add_f32_e32 v67, v78, v67
	v_pk_mul_f32 v[70:71], v[84:85], v[84:85]
	v_add_f32_e32 v66, v69, v66
	v_add_f32_e32 v67, v79, v67
	v_add_f32_e32 v66, v70, v66
	v_add_f32_e32 v67, v76, v67
	v_pk_mul_f32 v[72:73], v[86:87], v[86:87]
	v_add_f32_e32 v66, v71, v66
	v_add_f32_e32 v67, v77, v67
	v_add_f32_e32 v66, v72, v66
	v_add_f32_e32 v67, v74, v67
	v_add_f32_e32 v66, v73, v66
	v_add_f32_e32 v67, v75, v67
	v_add_f32_e32 v66, v67, v66
	ds_bpermute_b32 v67, v161, v66
	s_waitcnt lgkmcnt(0)
	v_add_f32_e32 v66, v66, v67
	ds_bpermute_b32 v67, v160, v66
	s_and_saveexec_b64 s[28:29], s[38:39]
	s_cbranch_execz .LBB0_484
	v_readlane_b32 s58, v252, 43
	v_lshlrev_b64 v[68:69], 6, v[82:83]
	v_readlane_b32 s59, v252, 44
	s_waitcnt lgkmcnt(0)
	v_add_f32_e32 v66, v66, v67
	v_lshl_add_u64 v[68:69], s[58:59], 0, v[68:69]
	v_lshl_add_u64 v[68:69], s[52:53], 2, v[68:69]
	s_lshl_b32 s58, s91, 2
	s_mov_b32 s59, s95
	v_lshl_add_u64 v[68:69], v[68:69], 0, s[58:59]
	global_store_dword v[68:69], v66, off nt
